# global attention item prologue: Q/bound/K/V loads issued together with counted vmcnt instead of 4 serialized vmcnt(0)
# speedup vs baseline: 1.0043x; 1.0043x over previous
; DI void attn_item(const Params& p, int layer, int item, char* smem) {
;     ...
;   const int qpos = qpos0 + wid * 32 + l32;
;   bf16x8 qf[4];
; #pragma unroll
;   for (int s = 0; s < 4; ++s) qf[s] = *(const bf16x8*)(Qb + (size_t)qpos * 64 + s * 16 + h * 8);
;   f32x16 o0, o1;
; #pragma unroll
;   for (int r = 0; r < 16; ++r) { o0[r] = 0.f; o1[r] = 0.f; }
;   const int btype = (mode == 3) ? (hh < 6 ? 0 : (hh < 10 ? 1 : 2)) : (mode == 0 ? 2 : (mode == 1 ? 1 : 0));
;   float m_fix = p.bounds[layer * 8 + btype];
;   if (mode == 1) m_fix += p.bounds[layer * 8 + 4 + hh];
;   f32x16 cinit, lacc;
; #pragma unroll
;   for (int r = 0; r < 16; ++r) { cinit[r] = -m_fix; lacc[r] = 0.f; }
;   const bf16x8 ones = {(short)0x3F80, (short)0x3F80, (short)0x3F80, (short)0x3F80, (short)0x3F80, (short)0x3F80, (short)0x3F80, (short)0x3F80};
;   const int lr = tid >> 3, lc = tid & 7;
;   uint4 ka0, va0, kb0, vb0;
;     ...
;   AGLOAD(ka0, va0, TILE_OF(0));
;   if (n_it > 1) { AGLOAD(kb0, vb0, TILE_OF(1)); }
;   ASWRITE(ka0, va0, 0);
;   if (n_it > 2) { AGLOAD(ka0, va0, TILE_OF(2)); }
;   __syncthreads();
.LBB0_259:
	s_mul_hi_i32 s0, s14, 0x2aaaaaab
	s_lshr_b32 s1, s0, 31
	s_ashr_i32 s5, s0, 4
	s_add_i32 s5, s5, s1
	s_mul_i32 s0, s5, 0x60
	s_sub_i32 s0, s14, s0
	v_mov_b32_e32 v32, v213
	s_ashr_i32 s4, s0, 4
	s_lshl_b32 s0, s0, 8
	s_and_b32 s8, s0, 0xf00
	s_lshl_b32 s0, s5, 5
	v_ashrrev_i32_e32 v0, 1, v32
	s_add_i32 s1, s4, s0
	s_mul_i32 s2, s4, 0x56
	v_and_b32_e32 v0, 0xffffffe0, v0
	v_and_b32_e32 v36, 31, v32
	s_bfe_u32 s3, s2, 0x1000f
	s_bfe_u32 s2, s2, 0x80008
	s_add_i32 s1, s1, 22
	v_add_u32_e32 v0, s8, v0
	s_add_i32 s2, s2, s3
	s_mul_hi_i32 s3, s1, 0x88000
	s_mul_i32 s1, s1, 0x88000
	v_or_b32_e32 v134, v0, v36
	s_add_u32 s6, s88, s1
	v_ashrrev_i32_e32 v135, 31, v134
	v_bfe_u32 v140, v32, 5, 1
	s_addc_u32 s7, s89, s3
	v_lshlrev_b64 v[2:3], 7, v[134:135]
	v_lshl_add_u64 v[2:3], s[6:7], 0, v[2:3]
	v_lshlrev_b32_e32 v18, 4, v140
	v_mov_b32_e32 v19, v1
	v_readlane_b32 s6, v254, 50
	v_lshl_add_u64 v[2:3], v[2:3], 0, v[18:19]
	v_readlane_b32 s7, v254, 51
	global_load_dwordx4 v[98:101], v[2:3], off
	global_load_dwordx4 v[102:105], v[2:3], off offset:32
	global_load_dwordx4 v[106:109], v[2:3], off offset:64
	global_load_dwordx4 v[110:113], v[2:3], off offset:96
	s_sext_i32_i8 s2, s2
	global_load_dword v2, v1, s[6:7] offset:8
	s_add_i32 s2, s0, s2
	s_mul_i32 s3, s2, 0x88000
	s_add_i32 s0, s2, 28
	s_mul_hi_i32 s1, s0, 0x88000
	s_add_i32 s0, s3, 0xee0000
	v_ashrrev_i32_e32 v30, 3, v32
	s_add_u32 s0, s88, s0
	v_ashrrev_i32_e32 v31, 31, v30
	s_addc_u32 s1, s89, s1
	v_lshlrev_b32_e32 v19, 4, v32
	v_lshlrev_b64 v[20:21], 7, v[30:31]
	v_lshl_add_u64 v[136:137], s[0:1], 0, v[20:21]
	s_mov_b32 s6, 0x80000
	s_add_i32 s2, s2, 30
	s_add_i32 s3, s3, 0xff0000
	s_mul_hi_i32 s9, s2, 0x88000
	s_add_u32 s2, s88, s3
	s_addc_u32 s3, s89, s9
	v_mov_b64_e32 v[26:27], s[2:3]
	v_mad_i64_i32 v[138:139], s[2:3], v30, s28, v[26:27]
	s_movk_i32 s3, 0x90
	s_mov_b32 s2, 0x82000
	v_mul_lo_u32 v30, v30, s3
	v_add_u32_e32 v30, 16, v30
	v_add_u32_e32 v144, 16, v18
	v_mul_u32_u24_e32 v145, 0x90, v36
	v_mad_u32_u24 v146, v36, s3, v144
	v_and_b32_e32 v0, 0x70, v19
	v_lshl_add_u64 v[34:35], v[136:137], 0, v[0:1]
	v_add_co_u32_e32 v22, vcc, s6, v34
	v_add_u32_e32 v135, v30, v0
	s_nop 0
	v_addc_co_u32_e32 v23, vcc, 0, v35, vcc
	global_load_dwordx4 v[22:25], v[22:23], off
	v_add_co_u32_e32 v26, vcc, s2, v34
	v_lshl_add_u64 v[74:75], v[138:139], 0, v[0:1]
	s_nop 0
	v_addc_co_u32_e32 v27, vcc, 0, v35, vcc
	global_load_dwordx4 v[26:29], v[26:27], off
	s_movk_i32 s2, 0x2000
	v_lshlrev_b32_e32 v78, 3, v32
	v_and_b32_e32 v78, 8, v78
	v_and_or_b32 v19, v19, s74, v78
	v_add_co_u32_e32 v78, vcc, s2, v74
	v_add_u32_e32 v19, v30, v19
	s_nop 0
	v_addc_co_u32_e32 v79, vcc, 0, v75, vcc
	global_load_dwordx4 v[30:33], v[78:79], off
	s_mov_b32 s2, 0x84000
	v_add_co_u32_e32 v80, vcc, s2, v34
	v_add_u32_e32 v141, 0x2000, v19
	s_nop 0
	v_addc_co_u32_e32 v81, vcc, 0, v35, vcc
	global_load_dwordx4 v[66:69], v[80:81], off
	global_load_dwordx4 v[70:73], v[78:79], off offset:256
	v_lshl_add_u64 v[80:81], s[0:1], 0, v[0:1]
	v_lshl_add_u64 v[76:77], v[80:81], 0, v[20:21]
	s_mov_b32 s0, 0x86000
	v_add_u32_e32 v143, 0x6800, v19
	s_waitcnt vmcnt(5)
	v_xor_b32_e32 v2, 0x80000000, v2
	v_mov_b32_e32 v3, v2
	v_mov_b32_e32 v4, v2
	v_mov_b32_e32 v5, v2
	v_mov_b32_e32 v6, v2
	v_mov_b32_e32 v7, v2
	v_mov_b32_e32 v8, v2
	v_mov_b32_e32 v9, v2
	v_mov_b32_e32 v10, v2
	v_mov_b32_e32 v11, v2
	v_mov_b32_e32 v12, v2
	v_mov_b32_e32 v13, v2
	v_mov_b32_e32 v14, v2
	v_mov_b32_e32 v15, v2
	v_mov_b32_e32 v16, v2
	v_mov_b32_e32 v17, v2
	s_waitcnt vmcnt(4)
	ds_write_b128 v135, v[22:25]
	s_waitcnt vmcnt(2)
	ds_write2_b64 v141, v[30:31], v[32:33] offset0:128 offset1:130
	v_mad_u32_u24 v30, v36, s3, 16
	v_add_u32_e32 v142, v30, v18
	global_load_dwordx4 v[30:33], v[78:79], off offset:128
	v_add_co_u32_e32 v18, vcc, s0, v76
	s_waitcnt lgkmcnt(0)
	s_barrier
	ds_write_b128 v135, v[26:29] offset:18432
	v_addc_co_u32_e32 v19, vcc, 0, v77, vcc
	s_waitcnt vmcnt(0)
	ds_write2_b64 v143, v[30:31], v[32:33] offset0:128 offset1:130
	global_load_dwordx4 v[114:117], v[18:19], off
	global_load_dwordx4 v[118:121], v[78:79], off offset:384
	ds_read_b128 v[34:37], v146
	ds_read_b128 v[38:41], v146 offset:32
	v_mov_b64_e32 v[132:133], s[94:95]
	v_mov_b64_e32 v[130:131], s[92:93]
	s_waitcnt lgkmcnt(1)
	v_mfma_f32_32x32x16_bf16 v[18:33], v[34:37], v[98:101], v[2:17]
	ds_read_b128 v[34:37], v146 offset:64
	ds_read_b128 v[50:53], v146 offset:4608
	s_waitcnt lgkmcnt(2)
	v_mfma_f32_32x32x16_bf16 v[18:33], v[38:41], v[102:105], v[18:33]
	s_waitcnt lgkmcnt(1)
	v_mfma_f32_32x32x16_bf16 v[18:33], v[34:37], v[106:109], v[18:33]
	ds_read_b128 v[34:37], v146 offset:96
	s_waitcnt lgkmcnt(0)
	v_mfma_f32_32x32x16_bf16 v[18:33], v[34:37], v[110:113], v[18:33]
	v_mfma_f32_32x32x16_bf16 v[34:49], v[50:53], v[98:101], v[2:17]
	ds_read_b128 v[50:53], v146 offset:4640
	s_nop 9
	v_exp_f32_e32 v18, v18
	v_exp_f32_e32 v19, v19
	v_exp_f32_e32 v20, v20
	v_exp_f32_e32 v21, v21
	v_exp_f32_e32 v22, v22
	v_exp_f32_e32 v23, v23
	s_waitcnt lgkmcnt(0)
	v_mfma_f32_32x32x16_bf16 v[34:49], v[50:53], v[102:105], v[34:49]
	ds_read_b128 v[50:53], v146 offset:4672
	v_exp_f32_e32 v24, v24
	v_exp_f32_e32 v25, v25
	v_cvt_pk_bf16_f32 v18, v18, v19
	v_cvt_pk_bf16_f32 v19, v20, v21
	v_cvt_pk_bf16_f32 v20, v22, v23
	v_cvt_pk_bf16_f32 v21, v24, v25
	s_waitcnt lgkmcnt(0)
	v_mfma_f32_32x32x16_bf16 v[34:49], v[50:53], v[106:109], v[34:49]
	ds_read_b128 v[50:53], v146 offset:4704
	ds_read_b128 v[22:25], v142 offset:9216
	ds_read_b128 v[78:81], v142 offset:9248
	v_exp_f32_e32 v82, v26
	v_exp_f32_e32 v83, v27
	v_exp_f32_e32 v84, v28
	v_exp_f32_e32 v85, v29
	v_exp_f32_e32 v122, v30
	s_waitcnt lgkmcnt(2)
; DI void attn_item(const Params& p, int layer, int item, char* smem) {
;     ...
;       f32x16 S[2];
; #pragma unroll
;       for (int kt = 0; kt < 2; ++kt) {
; #pragma unroll
;         for (int s = 0; s < 4; ++s) {
;           bf16x8 kf = *(const bf16x8*)(sK + (kt * 32 + l32) * KROW + s * 32 + h * 16);
;           S[kt] = MFMA32(kf, qf[s], s == 0 ? cinit : S[kt]);
;         }
;       }
;       if (tile < 64 && maskmode == 1) {
;         int qr = tq >> 6, qc = tq & 63;
;         int ws = min(max(qc - 8, 0), 48);
;         int dr = tile - qr + 7;
; #pragma unroll
;         for (int kt = 0; kt < 2; ++kt)
; #pragma unroll
;           for (int r = 0; r < 16; ++r) {
;             int kc = kt * 32 + crow(r, h);
;             bool ok = (unsigned)(kc - ws) < 16u;
;             int bi = ok ? (dr * 31 + kc - qc + 15) : 0;
;             float bv = s_rpb[bi];
;             S[kt][r] = ok ? (S[kt][r] + bv) : -INFINITY;
;           }
;       } else if (tile < 64 && maskmode == 2) {
; #pragma unroll
;         for (int kt = 0; kt < 2; ++kt)
; #pragma unroll
;           for (int r = 0; r < 16; ++r) {
;             int tk = tile * 64 + kt * 32 + crow(r, h);
;             int dd = tq - tk;
;             bool ok = (dd <= 128) && (dd >= -128);
;             S[kt][r] = ok ? S[kt][r] : -INFINITY;
;           }
;       }
; #pragma unroll
;       for (int r = 0; r < 16; ++r) {
;         S[0][r] = __builtin_amdgcn_exp2f(S[0][r]);
;         S[1][r] = __builtin_amdgcn_exp2f(S[1][r]);
;       }
; #pragma unroll
;       for (int kt = 0; kt < 2; ++kt)
; #pragma unroll
;         for (int s2 = 0; s2 < 2; ++s2) {
;           uint4 pw;
;           pw.x = pack_bf16(S[kt][8 * s2 + 0], S[kt][8 * s2 + 1]);
;           pw.y = pack_bf16(S[kt][8 * s2 + 2], S[kt][8 * s2 + 3]);
;           pw.z = pack_bf16(S[kt][8 * s2 + 4], S[kt][8 * s2 + 5]);
;           pw.w = pack_bf16(S[kt][8 * s2 + 6], S[kt][8 * s2 + 7]);
;           bf16x8 pf = __builtin_bit_cast(bf16x8, pw);
;           const int koff = (kt * 32 + 16 * s2 + 8 * h) * 2;
;           {
;             bf16x8 vf = *(const bf16x8*)(sV + l32 * VROW + koff);
;             o0 = MFMA32(vf, pf, o0);
;             lacc = MFMA32(ones, pf, lacc);
;           }
;           {
;             bf16x8 vf = *(const bf16x8*)(sV + (32 + l32) * VROW + koff);
;             o1 = MFMA32(vf, pf, o1);
;           }
;         }
;     ...
;   for (int it = 0; it < n_it; it += 2) {
	v_mfma_f32_32x32x16_bf16 v[34:49], v[50:53], v[110:113], v[34:49]
	v_exp_f32_e32 v124, v31
	v_exp_f32_e32 v126, v32
	v_exp_f32_e32 v128, v33
	v_cvt_pk_bf16_f32 v82, v82, v83
	v_cvt_pk_bf16_f32 v83, v84, v85
	v_cvt_pk_bf16_f32 v84, v122, v124
	v_cvt_pk_bf16_f32 v85, v126, v128
	s_nop 4
	v_exp_f32_e32 v86, v34
	v_exp_f32_e32 v87, v35
	v_exp_f32_e32 v88, v36
	v_exp_f32_e32 v89, v37
	v_exp_f32_e32 v90, v38
	v_exp_f32_e32 v91, v39
	v_exp_f32_e32 v92, v40
	v_exp_f32_e32 v93, v41
	v_exp_f32_e32 v94, v42
	v_exp_f32_e32 v95, v43
	v_exp_f32_e32 v96, v44
	v_exp_f32_e32 v97, v45
	v_exp_f32_e32 v123, v46
	v_exp_f32_e32 v125, v47
	v_exp_f32_e32 v127, v48
	v_exp_f32_e32 v129, v49
	s_waitcnt lgkmcnt(1)
	v_mfma_f32_32x32x16_bf16 v[34:49], v[22:25], v[18:21], 0
	ds_read_b128 v[22:25], v142 offset:13824
	s_waitcnt lgkmcnt(1)
	v_mfma_f32_32x32x16_bf16 v[34:49], v[78:81], v[82:85], v[34:49]
	ds_read_b128 v[78:81], v142 offset:13856
	v_mfma_f32_32x32x16_bf16 v[50:65], v[130:133], v[18:21], 0
	s_waitcnt lgkmcnt(1)
	v_mfma_f32_32x32x16_bf16 v[18:33], v[22:25], v[18:21], 0
	v_mfma_f32_32x32x16_bf16 v[50:65], v[130:133], v[82:85], v[50:65]
	s_waitcnt lgkmcnt(0)
	v_mfma_f32_32x32x16_bf16 v[18:33], v[78:81], v[82:85], v[18:33]
	ds_read_b128 v[82:85], v142 offset:9280
	v_cvt_pk_bf16_f32 v78, v86, v87
	v_cvt_pk_bf16_f32 v79, v88, v89
	v_cvt_pk_bf16_f32 v80, v90, v91
	v_cvt_pk_bf16_f32 v81, v92, v93
	s_waitcnt lgkmcnt(0)
	s_nop 0
	v_mfma_f32_32x32x16_bf16 v[34:49], v[82:85], v[78:81], v[34:49]
	ds_read_b128 v[82:85], v142 offset:13888
	s_waitcnt lgkmcnt(0)
	v_mfma_f32_32x32x16_bf16 v[18:33], v[82:85], v[78:81], v[18:33]
	ds_read_b128 v[82:85], v142 offset:9312
	v_mfma_f32_32x32x16_bf16 v[50:65], v[130:133], v[78:81], v[50:65]
	v_cvt_pk_bf16_f32 v78, v94, v95
	v_cvt_pk_bf16_f32 v79, v96, v97
	v_cvt_pk_bf16_f32 v80, v123, v125
	v_cvt_pk_bf16_f32 v81, v127, v129
	s_waitcnt lgkmcnt(0)
	s_nop 0
	v_mfma_f32_32x32x16_bf16 v[34:49], v[82:85], v[78:81], v[34:49]
	ds_read_b128 v[82:85], v142 offset:13920
	s_waitcnt lgkmcnt(0)
	s_barrier
	ds_write_b128 v135, v[66:69]
	ds_write2_b64 v141, v[70:71], v[72:73] offset0:128 offset1:130
	global_load_dwordx4 v[122:125], v[76:77], off
	global_load_dwordx4 v[126:129], v[74:75], off
	v_mfma_f32_32x32x16_bf16 v[50:65], v[130:133], v[78:81], v[50:65]
	v_mfma_f32_32x32x16_bf16 v[18:33], v[82:85], v[78:81], v[18:33]
	ds_read_b128 v[82:85], v146 offset:18432
	ds_read_b128 v[86:89], v146 offset:18464
	s_mov_b32 s2, 2
	v_add_u32_e32 v144, v144, v145
	s_waitcnt lgkmcnt(1)
	v_mfma_f32_32x32x16_bf16 v[66:81], v[82:85], v[98:101], v[2:17]
	ds_read_b128 v[82:85], v146 offset:18496
	ds_read_b128 v[148:151], v146 offset:23040
	s_waitcnt lgkmcnt(2)
	v_mfma_f32_32x32x16_bf16 v[66:81], v[86:89], v[102:105], v[66:81]
	s_waitcnt lgkmcnt(1)
	v_mfma_f32_32x32x16_bf16 v[66:81], v[82:85], v[106:109], v[66:81]
	ds_read_b128 v[82:85], v146 offset:18528
	s_waitcnt lgkmcnt(0)
	v_mfma_f32_32x32x16_bf16 v[66:81], v[82:85], v[110:113], v[66:81]
	v_mfma_f32_32x32x16_bf16 v[82:97], v[148:151], v[98:101], v[2:17]
	ds_read_b128 v[148:151], v146 offset:23072
	s_nop 9
	v_exp_f32_e32 v66, v66
	v_exp_f32_e32 v67, v67
	v_exp_f32_e32 v68, v68
	v_exp_f32_e32 v69, v69
	v_exp_f32_e32 v70, v70
	v_exp_f32_e32 v71, v71
	s_waitcnt lgkmcnt(0)
	v_mfma_f32_32x32x16_bf16 v[82:97], v[148:151], v[102:105], v[82:97]
	ds_read_b128 v[148:151], v146 offset:23104
	v_exp_f32_e32 v72, v72
	v_exp_f32_e32 v73, v73
	v_cvt_pk_bf16_f32 v66, v66, v67
	v_cvt_pk_bf16_f32 v67, v68, v69
	v_cvt_pk_bf16_f32 v68, v70, v71
	v_cvt_pk_bf16_f32 v69, v72, v73
	s_waitcnt lgkmcnt(0)
	v_mfma_f32_32x32x16_bf16 v[82:97], v[148:151], v[106:109], v[82:97]
	ds_read_b128 v[146:149], v146 offset:23136
	v_exp_f32_e32 v78, v78
	v_exp_f32_e32 v79, v79
	v_exp_f32_e32 v80, v80
	v_exp_f32_e32 v81, v81
	s_waitcnt lgkmcnt(0)
	v_mfma_f32_32x32x16_bf16 v[82:97], v[146:149], v[110:113], v[82:97]
	v_exp_f32_e32 v146, v74
	v_exp_f32_e32 v147, v75
	v_exp_f32_e32 v148, v76
	v_exp_f32_e32 v149, v77
	ds_read_b128 v[70:73], v142 offset:27648
	ds_read_b128 v[74:77], v142 offset:27680
	s_nop 5
	v_exp_f32_e32 v82, v82
	s_waitcnt lgkmcnt(1)
	v_mfma_f32_32x32x16_bf16 v[34:49], v[70:73], v[66:69], v[34:49]
	ds_read_b128 v[70:73], v142 offset:32256
	v_exp_f32_e32 v83, v83
	v_exp_f32_e32 v84, v84
	v_exp_f32_e32 v85, v85
	v_exp_f32_e32 v86, v86
	v_exp_f32_e32 v87, v87
	v_exp_f32_e32 v88, v88
	s_waitcnt lgkmcnt(0)
	v_mfma_f32_32x32x16_bf16 v[18:33], v[70:73], v[66:69], v[18:33]
	ds_read_b128 v[70:73], v142 offset:32288
	v_exp_f32_e32 v89, v89
	v_exp_f32_e32 v90, v90
	v_exp_f32_e32 v91, v91
	v_exp_f32_e32 v92, v92
	v_exp_f32_e32 v93, v93
	v_exp_f32_e32 v94, v94
	v_mfma_f32_32x32x16_bf16 v[50:65], v[130:133], v[66:69], v[50:65]
	v_cvt_pk_bf16_f32 v66, v146, v147
	v_cvt_pk_bf16_f32 v67, v148, v149
	v_cvt_pk_bf16_f32 v68, v78, v79
	v_cvt_pk_bf16_f32 v69, v80, v81
	v_exp_f32_e32 v95, v95
	v_exp_f32_e32 v96, v96
	v_exp_f32_e32 v97, v97
	s_waitcnt lgkmcnt(0)
	v_mfma_f32_32x32x16_bf16 v[18:33], v[70:73], v[66:69], v[18:33]
	ds_read_b128 v[70:73], v142 offset:27712
	v_mfma_f32_32x32x16_bf16 v[34:49], v[74:77], v[66:69], v[34:49]
	v_mfma_f32_32x32x16_bf16 v[50:65], v[130:133], v[66:69], v[50:65]
	v_cvt_pk_bf16_f32 v66, v82, v83
	v_cvt_pk_bf16_f32 v67, v84, v85
	v_cvt_pk_bf16_f32 v68, v86, v87
	v_cvt_pk_bf16_f32 v69, v88, v89
	s_waitcnt lgkmcnt(0)
	s_nop 0
	v_mfma_f32_32x32x16_bf16 v[34:49], v[70:73], v[66:69], v[34:49]
	ds_read_b128 v[70:73], v142 offset:32320
	s_waitcnt lgkmcnt(0)
	v_mfma_f32_32x32x16_bf16 v[18:33], v[70:73], v[66:69], v[18:33]
	ds_read_b128 v[70:73], v142 offset:27744
	v_mfma_f32_32x32x16_bf16 v[50:65], v[130:133], v[66:69], v[50:65]
	v_cvt_pk_bf16_f32 v66, v90, v91
	v_cvt_pk_bf16_f32 v67, v92, v93
	v_cvt_pk_bf16_f32 v68, v94, v95
	v_cvt_pk_bf16_f32 v69, v96, v97
	s_waitcnt lgkmcnt(0)
	s_nop 0
	v_mfma_f32_32x32x16_bf16 v[34:49], v[70:73], v[66:69], v[34:49]
	ds_read_b128 v[70:73], v142 offset:32352
	s_waitcnt lgkmcnt(0)
	s_barrier
	v_mfma_f32_32x32x16_bf16 v[50:65], v[130:133], v[66:69], v[50:65]
	v_mfma_f32_32x32x16_bf16 v[18:33], v[70:73], v[66:69], v[18:33]
	s_nop 11
	v_mov_b32_e32 v51, 0
	v_mov_b32_e32 v52, 0
	s_branch .LBB0_261
